# plus rotary-table loop: positions lines of the ten iterations touched up front
# speedup vs baseline: 1.0138x; 1.0138x over previous
; __global__ void __launch_bounds__(512, 2) hybrid_fwd(Args unused_args) {
;     ...
;       float* r16 = (float*)(ws + WS_ROPE16); float* r64 = (float*)(ws + WS_ROPE64);
;       for (int i = bid * 512 + tid; i < T * 40; i += G * 512) { const int row = i / 40, k = i % 40; const float pos = (float)a.pos[row];
;           const float inv = k < 8 ? exp2f(-(float)(2 * k) * (13.287712379549449f / 16.0f)) : exp2f(-(float)(2 * (k - 8)) * (13.287712379549449f / 64.0f));
;           const float ang = pos * inv; double ad = (double)ang; ad -= 6.283185307179586 * rint(ad * 0.15915494309189535); const float ar = (float)ad; const float sn = __sinf(ar), cs = __cosf(ar);
;           if (k < 8) { r16[(size_t)row * 16 + 2 * k] = cs; r16[(size_t)row * 16 + 2 * k + 1] = sn; } else { r64[(size_t)row * 64 + 2 * (k - 8)] = cs; r64[(size_t)row * 64 + 2 * (k - 8) + 1] = sn; } } }
.Lmy_xconv_done:
	v_lshl_add_u32 v2, s36, 9, v2
	s_mov_b32 s1, 0x140000
	v_cmp_gt_i32_e32 vcc, s1, v2
	s_and_saveexec_b64 s[2:3], vcc
	s_cbranch_execz .LBB0_595
	s_add_u32 s6, s28, 0x1b00000
	s_mov_b32 s10, 0x6dc9c883
	s_mov_b32 s12, 0x54442d18
	s_addc_u32 s7, s29, 0
	s_lshl_b32 s1, s30, 9
	v_lshlrev_b32_e32 v4, 1, v2
	s_lshl_b32 s14, s30, 10
	s_mov_b64 s[8:9], 0
	s_mov_b32 s15, 0x66666667
	s_movk_i32 s16, 0xffd8
	s_movk_i32 s17, 0xffb0
	s_mov_b32 s18, 0xc2fc0000
	v_not_b32_e32 v3, 63
	v_mov_b32_e32 v5, 0x42800000
	s_mov_b32 s11, 0x3fc45f30
	s_mov_b32 s13, 0xc01921fb
	v_mov_b32_e32 v12, 0
	s_mov_b32 s19, 0x13ffff
	s_cmpk_eq_u32 s30, 0x100
	s_cbranch_scc0 .Lmy_rope_go
	v_mov_b32_e32 v110, v2
	v_mul_hi_i32 v111, v110, s15
	v_lshrrev_b32_e32 v113, 31, v111
	v_ashrrev_i32_e32 v111, 4, v111
	v_add_u32_e32 v112, v111, v113
	v_ashrrev_i32_e32 v113, 31, v112
	v_lshl_add_u64 v[126:127], v[112:113], 2, s[26:27]
	global_load_dword v114, v[126:127], off
	v_add_u32_e32 v110, s1, v110
	v_mul_hi_i32 v111, v110, s15
	v_lshrrev_b32_e32 v113, 31, v111
	v_ashrrev_i32_e32 v111, 4, v111
	v_add_u32_e32 v112, v111, v113
	v_ashrrev_i32_e32 v113, 31, v112
	v_lshl_add_u64 v[126:127], v[112:113], 2, s[26:27]
	global_load_dword v115, v[126:127], off
	v_add_u32_e32 v110, s1, v110
	v_mul_hi_i32 v111, v110, s15
	v_lshrrev_b32_e32 v113, 31, v111
	v_ashrrev_i32_e32 v111, 4, v111
	v_add_u32_e32 v112, v111, v113
	v_ashrrev_i32_e32 v113, 31, v112
	v_lshl_add_u64 v[126:127], v[112:113], 2, s[26:27]
	global_load_dword v116, v[126:127], off
	v_add_u32_e32 v110, s1, v110
	v_mul_hi_i32 v111, v110, s15
	v_lshrrev_b32_e32 v113, 31, v111
	v_ashrrev_i32_e32 v111, 4, v111
	v_add_u32_e32 v112, v111, v113
	v_ashrrev_i32_e32 v113, 31, v112
	v_lshl_add_u64 v[126:127], v[112:113], 2, s[26:27]
	global_load_dword v117, v[126:127], off
	v_add_u32_e32 v110, s1, v110
	v_mul_hi_i32 v111, v110, s15
	v_lshrrev_b32_e32 v113, 31, v111
	v_ashrrev_i32_e32 v111, 4, v111
	v_add_u32_e32 v112, v111, v113
	v_ashrrev_i32_e32 v113, 31, v112
	v_lshl_add_u64 v[126:127], v[112:113], 2, s[26:27]
	global_load_dword v118, v[126:127], off
	v_add_u32_e32 v110, s1, v110
	v_mul_hi_i32 v111, v110, s15
	v_lshrrev_b32_e32 v113, 31, v111
	v_ashrrev_i32_e32 v111, 4, v111
	v_add_u32_e32 v112, v111, v113
	v_ashrrev_i32_e32 v113, 31, v112
	v_lshl_add_u64 v[126:127], v[112:113], 2, s[26:27]
	global_load_dword v119, v[126:127], off
	v_add_u32_e32 v110, s1, v110
	v_mul_hi_i32 v111, v110, s15
	v_lshrrev_b32_e32 v113, 31, v111
	v_ashrrev_i32_e32 v111, 4, v111
	v_add_u32_e32 v112, v111, v113
	v_ashrrev_i32_e32 v113, 31, v112
	v_lshl_add_u64 v[126:127], v[112:113], 2, s[26:27]
	global_load_dword v120, v[126:127], off
	v_add_u32_e32 v110, s1, v110
	v_mul_hi_i32 v111, v110, s15
	v_lshrrev_b32_e32 v113, 31, v111
	v_ashrrev_i32_e32 v111, 4, v111
	v_add_u32_e32 v112, v111, v113
	v_ashrrev_i32_e32 v113, 31, v112
	v_lshl_add_u64 v[126:127], v[112:113], 2, s[26:27]
	global_load_dword v121, v[126:127], off
	v_add_u32_e32 v110, s1, v110
	v_mul_hi_i32 v111, v110, s15
	v_lshrrev_b32_e32 v113, 31, v111
	v_ashrrev_i32_e32 v111, 4, v111
	v_add_u32_e32 v112, v111, v113
	v_ashrrev_i32_e32 v113, 31, v112
	v_lshl_add_u64 v[126:127], v[112:113], 2, s[26:27]
	global_load_dword v122, v[126:127], off
	v_add_u32_e32 v110, s1, v110
	v_mul_hi_i32 v111, v110, s15
	v_lshrrev_b32_e32 v113, 31, v111
	v_ashrrev_i32_e32 v111, 4, v111
	v_add_u32_e32 v112, v111, v113
	v_ashrrev_i32_e32 v113, 31, v112
	v_lshl_add_u64 v[126:127], v[112:113], 2, s[26:27]
	global_load_dword v123, v[126:127], off
.Lmy_rope_go:
	s_branch .LBB0_587
.LBB0_586:
	s_or_b64 exec, exec, s[4:5]
	v_add_u32_e32 v2, s1, v2
	v_cmp_lt_i32_e32 vcc, s19, v2
	s_or_b64 s[8:9], vcc, s[8:9]
	v_add_u32_e32 v4, s14, v4
	s_andn2_b64 exec, exec, s[8:9]
	s_cbranch_execz .LBB0_595
